# GU GEMM: peeled first k-iteration (SrcC=0 instead of zeroing 128 acc regs; vmcnt(16) in its first two segments)
# speedup vs baseline: 1.0871x; 1.0136x over previous
.LBB0_1445:
	s_ashr_i32 s11, s10, 31
	s_lshl_b64 s[12:13], s[10:11], 19
	v_readlane_b32 s14, v254, 28
	v_readlane_b32 s15, v254, 29
	s_add_u32 s12, s14, s12
	s_addc_u32 s13, s15, s13
	s_and_b64 s[14:15], s[0:1], exec
	s_cselect_b32 s11, s13, s5
	s_cselect_b32 s37, s12, s4
	s_ashr_i32 s9, s8, 31
	s_lshl_b64 s[14:15], s[8:9], 19
	s_add_u32 s14, s20, s14
	s_addc_u32 s15, s21, s15
	s_and_b64 s[18:19], s[0:1], exec
	s_cselect_b32 s9, s15, s17
	s_cselect_b32 s38, s14, s16
	s_add_u32 s4, s4, 0x40080
	s_addc_u32 s5, s5, 0
	s_add_u32 s39, s16, 0x100
	s_addc_u32 s40, s17, 0
	s_mov_b32 s41, -2
	s_add_u32 s16, s4, 0xfffc0080
	s_addc_u32 s17, s5, -1
	s_add_i32 s42, 0, 0x10000
	s_cmp_eq_u32 s41, 12
	s_cselect_b32 s19, s11, s17
	s_cselect_b32 s18, s37, s16
	s_cselect_b32 s17, s9, s40
	s_cselect_b32 s16, s38, s39
	s_add_i32 s44, 0, 0x14000
	v_add_u32_e32 v142, s42, v195
	v_add_u32_e32 v162, s44, v195
	ds_read_b128 v[130:133], v142
	ds_read_b128 v[134:137], v142 offset:1024
	ds_read_b128 v[138:141], v142 offset:2048
	ds_read_b128 v[142:145], v142 offset:3072
	ds_read_b128 v[146:149], v162
	ds_read_b128 v[150:153], v162 offset:1024
	ds_read_b128 v[174:177], v162 offset:2048
	ds_read_b128 v[178:181], v162 offset:3072
	v_lshl_add_u64 v[162:163], s[4:5], 0, v[170:171]
	s_add_i32 m0, s23, 0xc000
	ds_read_b128 v[182:185], v199
	ds_read_b128 v[186:189], v199 offset:1024
	ds_read_b128 v[200:203], v199 offset:2048
	ds_read_b128 v[204:207], v199 offset:3072
	ds_read_b128 v[220:223], v199 offset:4096
	ds_read_b128 v[224:227], v199 offset:5120
	ds_read_b128 v[228:231], v199 offset:6144
	ds_read_b128 v[232:235], v199 offset:7168
	global_load_lds_dwordx4 v[162:163], off
	v_lshl_add_u64 v[162:163], s[4:5], 0, v[172:173]
	s_add_i32 m0, s23, 0xe000
	s_nop 0
	global_load_lds_dwordx4 v[162:163], off
	s_waitcnt vmcnt(16)
	s_waitcnt lgkmcnt(0)
	s_barrier
	s_setprio 1
	s_waitcnt lgkmcnt(0)
	v_mfma_f32_16x16x32_bf16 v[126:129], v[130:133], v[182:185], 0
	v_mfma_f32_16x16x32_bf16 v[118:121], v[138:141], v[182:185], 0
	v_mfma_f32_16x16x32_bf16 v[110:113], v[130:133], v[200:203], 0
	v_mfma_f32_16x16x32_bf16 v[102:105], v[138:141], v[200:203], 0
	v_mfma_f32_16x16x32_bf16 v[94:97], v[130:133], v[220:223], 0
	v_mfma_f32_16x16x32_bf16 v[86:89], v[138:141], v[220:223], 0
	v_mfma_f32_16x16x32_bf16 v[78:81], v[130:133], v[228:231], 0
	v_mfma_f32_16x16x32_bf16 v[70:73], v[138:141], v[228:231], 0
	v_mfma_f32_16x16x32_bf16 v[126:129], v[134:137], v[186:189], v[126:129]
	v_mfma_f32_16x16x32_bf16 v[118:121], v[142:145], v[186:189], v[118:121]
	v_mfma_f32_16x16x32_bf16 v[110:113], v[134:137], v[204:207], v[110:113]
	v_mfma_f32_16x16x32_bf16 v[102:105], v[142:145], v[204:207], v[102:105]
	v_mfma_f32_16x16x32_bf16 v[94:97], v[134:137], v[224:227], v[94:97]
	v_mfma_f32_16x16x32_bf16 v[86:89], v[142:145], v[224:227], v[86:89]
	v_mfma_f32_16x16x32_bf16 v[78:81], v[134:137], v[232:235], v[78:81]
	v_mfma_f32_16x16x32_bf16 v[70:73], v[142:145], v[232:235], v[70:73]
	s_setprio 0
	s_setprio 1
	v_mfma_f32_16x16x32_bf16 v[122:125], v[146:149], v[182:185], 0
	v_mfma_f32_16x16x32_bf16 v[114:117], v[174:177], v[182:185], 0
	v_mfma_f32_16x16x32_bf16 v[106:109], v[146:149], v[200:203], 0
	v_mfma_f32_16x16x32_bf16 v[98:101], v[174:177], v[200:203], 0
	v_mfma_f32_16x16x32_bf16 v[90:93], v[146:149], v[220:223], 0
	v_mfma_f32_16x16x32_bf16 v[82:85], v[174:177], v[220:223], 0
	v_mfma_f32_16x16x32_bf16 v[74:77], v[146:149], v[228:231], 0
	v_mfma_f32_16x16x32_bf16 v[66:69], v[174:177], v[228:231], 0
	v_mfma_f32_16x16x32_bf16 v[122:125], v[150:153], v[186:189], v[122:125]
	v_mfma_f32_16x16x32_bf16 v[114:117], v[178:181], v[186:189], v[114:117]
	v_mfma_f32_16x16x32_bf16 v[106:109], v[150:153], v[204:207], v[106:109]
	v_mfma_f32_16x16x32_bf16 v[98:101], v[178:181], v[204:207], v[98:101]
	v_mfma_f32_16x16x32_bf16 v[90:93], v[150:153], v[224:227], v[90:93]
	v_mfma_f32_16x16x32_bf16 v[82:85], v[178:181], v[224:227], v[82:85]
	v_mfma_f32_16x16x32_bf16 v[74:77], v[150:153], v[232:235], v[74:77]
	v_mfma_f32_16x16x32_bf16 v[66:69], v[178:181], v[232:235], v[66:69]
	s_setprio 0
	s_barrier
	s_add_i32 s42, s42, s22
	v_lshl_add_u64 v[162:163], s[16:17], 0, v[0:1]
	s_mov_b32 m0, s42
	ds_read_b128 v[182:185], v199 offset:16384
	ds_read_b128 v[186:189], v199 offset:17408
	ds_read_b128 v[200:203], v199 offset:18432
	ds_read_b128 v[204:207], v199 offset:19456
	ds_read_b128 v[220:223], v199 offset:20480
	ds_read_b128 v[224:227], v199 offset:21504
	ds_read_b128 v[228:231], v199 offset:22528
	ds_read_b128 v[232:235], v199 offset:23552
	global_load_lds_dwordx4 v[162:163], off
	s_add_i32 m0, s42, 0x2000
	s_add_u32 s42, s16, 0x40000
	v_lshl_add_u64 v[190:191], s[16:17], 0, v[154:155]
	s_addc_u32 s43, s17, 0
	s_add_i32 s44, s44, s22
	global_load_lds_dwordx4 v[190:191], off
	v_lshl_add_u64 v[196:197], s[42:43], 0, v[0:1]
	s_mov_b32 m0, s44
	v_lshl_add_u64 v[208:209], s[18:19], 0, v[156:157]
	global_load_lds_dwordx4 v[196:197], off
	v_lshl_add_u64 v[196:197], s[42:43], 0, v[154:155]
	s_add_i32 m0, s44, 0x2000
	s_nop 0
	global_load_lds_dwordx4 v[196:197], off
	v_lshl_add_u64 v[196:197], s[18:19], 0, v[158:159]
	s_mov_b32 m0, s23
	s_nop 0
	global_load_lds_dwordx4 v[196:197], off
	s_mov_b32 m0, s26
	s_nop 0
	global_load_lds_dwordx4 v[208:209], off
	s_cmp_eq_u32 s34, 1
	s_cbranch_scc1 .Lgu_peel_w8
	s_waitcnt vmcnt(16)
	s_branch .Lgu_peel_wj
.Lgu_peel_w8:
	s_waitcnt vmcnt(8)
.Lgu_peel_wj:
	s_waitcnt lgkmcnt(0)
	s_barrier
	s_setprio 1
	s_waitcnt lgkmcnt(0)
	v_mfma_f32_16x16x32_bf16 v[62:65], v[130:133], v[182:185], 0
	v_mfma_f32_16x16x32_bf16 v[54:57], v[138:141], v[182:185], 0
	v_mfma_f32_16x16x32_bf16 v[46:49], v[130:133], v[200:203], 0
	v_mfma_f32_16x16x32_bf16 v[38:41], v[138:141], v[200:203], 0
	v_mfma_f32_16x16x32_bf16 v[30:33], v[130:133], v[220:223], 0
	v_mfma_f32_16x16x32_bf16 v[22:25], v[138:141], v[220:223], 0
	v_mfma_f32_16x16x32_bf16 v[14:17], v[130:133], v[228:231], 0
	v_mfma_f32_16x16x32_bf16 v[6:9], v[138:141], v[228:231], 0
	v_mfma_f32_16x16x32_bf16 v[62:65], v[134:137], v[186:189], v[62:65]
	v_mfma_f32_16x16x32_bf16 v[54:57], v[142:145], v[186:189], v[54:57]
	v_mfma_f32_16x16x32_bf16 v[46:49], v[134:137], v[204:207], v[46:49]
	v_mfma_f32_16x16x32_bf16 v[38:41], v[142:145], v[204:207], v[38:41]
	v_mfma_f32_16x16x32_bf16 v[30:33], v[134:137], v[224:227], v[30:33]
	v_mfma_f32_16x16x32_bf16 v[22:25], v[142:145], v[224:227], v[22:25]
	v_mfma_f32_16x16x32_bf16 v[14:17], v[134:137], v[232:235], v[14:17]
	v_mfma_f32_16x16x32_bf16 v[6:9], v[142:145], v[232:235], v[6:9]
	s_setprio 0
	s_setprio 1
	v_mfma_f32_16x16x32_bf16 v[58:61], v[146:149], v[182:185], 0
	v_mfma_f32_16x16x32_bf16 v[50:53], v[174:177], v[182:185], 0
	v_mfma_f32_16x16x32_bf16 v[42:45], v[146:149], v[200:203], 0
	v_mfma_f32_16x16x32_bf16 v[34:37], v[174:177], v[200:203], 0
	v_mfma_f32_16x16x32_bf16 v[26:29], v[146:149], v[220:223], 0
	v_mfma_f32_16x16x32_bf16 v[18:21], v[174:177], v[220:223], 0
	v_mfma_f32_16x16x32_bf16 v[10:13], v[146:149], v[228:231], 0
	v_mfma_f32_16x16x32_bf16 v[2:5], v[174:177], v[228:231], 0
	v_mfma_f32_16x16x32_bf16 v[58:61], v[150:153], v[186:189], v[58:61]
	v_mfma_f32_16x16x32_bf16 v[50:53], v[178:181], v[186:189], v[50:53]
	v_mfma_f32_16x16x32_bf16 v[42:45], v[150:153], v[204:207], v[42:45]
	v_mfma_f32_16x16x32_bf16 v[34:37], v[178:181], v[204:207], v[34:37]
	v_mfma_f32_16x16x32_bf16 v[26:29], v[150:153], v[224:227], v[26:29]
	v_mfma_f32_16x16x32_bf16 v[18:21], v[178:181], v[224:227], v[18:21]
	v_mfma_f32_16x16x32_bf16 v[10:13], v[150:153], v[232:235], v[10:13]
	v_mfma_f32_16x16x32_bf16 v[2:5], v[178:181], v[232:235], v[2:5]
	s_setprio 0
	s_barrier
	s_add_i32 s42, 0, 0x18000
	s_add_i32 s43, 0, 0x1c000
	v_add_u32_e32 v142, s42, v195
	v_add_u32_e32 v164, s43, v195
	ds_read_b128 v[130:133], v142
	ds_read_b128 v[134:137], v142 offset:1024
	ds_read_b128 v[138:141], v142 offset:2048
	ds_read_b128 v[142:145], v142 offset:3072
	ds_read_b128 v[146:149], v164
	ds_read_b128 v[150:153], v164 offset:1024
	ds_read_b128 v[174:177], v164 offset:2048
	ds_read_b128 v[178:181], v164 offset:3072
	s_add_u32 s18, s18, 0x40000
	s_addc_u32 s19, s19, 0
	s_mov_b32 m0, s27
	v_lshl_add_u64 v[214:215], s[18:19], 0, v[158:159]
	ds_read_b128 v[182:185], v199 offset:32768
	ds_read_b128 v[186:189], v199 offset:33792
	ds_read_b128 v[200:203], v199 offset:34816
	ds_read_b128 v[204:207], v199 offset:35840
	ds_read_b128 v[220:223], v199 offset:36864
	ds_read_b128 v[224:227], v199 offset:37888
	ds_read_b128 v[228:231], v199 offset:38912
	ds_read_b128 v[232:235], v199 offset:39936
	global_load_lds_dwordx4 v[214:215], off
	v_lshl_add_u64 v[214:215], s[18:19], 0, v[156:157]
	s_mov_b32 m0, s28
	s_nop 0
	global_load_lds_dwordx4 v[214:215], off
	s_waitcnt vmcnt(8)
	s_waitcnt lgkmcnt(0)
	s_barrier
	s_setprio 1
	s_waitcnt lgkmcnt(0)
	v_mfma_f32_16x16x32_bf16 v[126:129], v[130:133], v[182:185], v[126:129]
	v_mfma_f32_16x16x32_bf16 v[118:121], v[138:141], v[182:185], v[118:121]
	v_mfma_f32_16x16x32_bf16 v[110:113], v[130:133], v[200:203], v[110:113]
	v_mfma_f32_16x16x32_bf16 v[102:105], v[138:141], v[200:203], v[102:105]
	v_mfma_f32_16x16x32_bf16 v[94:97], v[130:133], v[220:223], v[94:97]
	v_mfma_f32_16x16x32_bf16 v[86:89], v[138:141], v[220:223], v[86:89]
	v_mfma_f32_16x16x32_bf16 v[78:81], v[130:133], v[228:231], v[78:81]
	v_mfma_f32_16x16x32_bf16 v[70:73], v[138:141], v[228:231], v[70:73]
	v_mfma_f32_16x16x32_bf16 v[126:129], v[134:137], v[186:189], v[126:129]
	v_mfma_f32_16x16x32_bf16 v[118:121], v[142:145], v[186:189], v[118:121]
	v_mfma_f32_16x16x32_bf16 v[110:113], v[134:137], v[204:207], v[110:113]
	v_mfma_f32_16x16x32_bf16 v[102:105], v[142:145], v[204:207], v[102:105]
	v_mfma_f32_16x16x32_bf16 v[94:97], v[134:137], v[224:227], v[94:97]
	v_mfma_f32_16x16x32_bf16 v[86:89], v[142:145], v[224:227], v[86:89]
	v_mfma_f32_16x16x32_bf16 v[78:81], v[134:137], v[232:235], v[78:81]
	v_mfma_f32_16x16x32_bf16 v[70:73], v[142:145], v[232:235], v[70:73]
	s_setprio 0
	s_setprio 1
	v_mfma_f32_16x16x32_bf16 v[122:125], v[146:149], v[182:185], v[122:125]
	v_mfma_f32_16x16x32_bf16 v[114:117], v[174:177], v[182:185], v[114:117]
	v_mfma_f32_16x16x32_bf16 v[106:109], v[146:149], v[200:203], v[106:109]
	v_mfma_f32_16x16x32_bf16 v[98:101], v[174:177], v[200:203], v[98:101]
	v_mfma_f32_16x16x32_bf16 v[90:93], v[146:149], v[220:223], v[90:93]
	v_mfma_f32_16x16x32_bf16 v[82:85], v[174:177], v[220:223], v[82:85]
	v_mfma_f32_16x16x32_bf16 v[74:77], v[146:149], v[228:231], v[74:77]
	v_mfma_f32_16x16x32_bf16 v[66:69], v[174:177], v[228:231], v[66:69]
	v_mfma_f32_16x16x32_bf16 v[122:125], v[150:153], v[186:189], v[122:125]
	v_mfma_f32_16x16x32_bf16 v[114:117], v[178:181], v[186:189], v[114:117]
	v_mfma_f32_16x16x32_bf16 v[106:109], v[150:153], v[204:207], v[106:109]
	v_mfma_f32_16x16x32_bf16 v[98:101], v[178:181], v[204:207], v[98:101]
	v_mfma_f32_16x16x32_bf16 v[90:93], v[150:153], v[224:227], v[90:93]
	v_mfma_f32_16x16x32_bf16 v[82:85], v[178:181], v[224:227], v[82:85]
	v_mfma_f32_16x16x32_bf16 v[74:77], v[150:153], v[232:235], v[74:77]
	v_mfma_f32_16x16x32_bf16 v[66:69], v[178:181], v[232:235], v[66:69]
	s_setprio 0
	s_barrier
	s_add_i32 s18, s42, s22
	v_lshl_add_u64 v[162:163], v[162:163], 0, s[86:87]
	s_mov_b32 m0, s18
	ds_read_b128 v[182:185], v199 offset:49152
	ds_read_b128 v[186:189], v199 offset:50176
	ds_read_b128 v[200:203], v199 offset:51200
	ds_read_b128 v[204:207], v199 offset:52224
	ds_read_b128 v[220:223], v199 offset:53248
	ds_read_b128 v[224:227], v199 offset:54272
	ds_read_b128 v[228:231], v199 offset:55296
	ds_read_b128 v[232:235], v199 offset:56320
	global_load_lds_dwordx4 v[162:163], off
	s_add_i32 m0, s18, 0x2000
	s_add_u32 s16, s16, 0x40080
	v_lshl_add_u64 v[162:163], v[190:191], 0, s[86:87]
	s_addc_u32 s17, s17, 0
	s_add_i32 s18, s43, s22
	global_load_lds_dwordx4 v[162:163], off
	v_lshl_add_u64 v[162:163], s[16:17], 0, v[0:1]
	s_mov_b32 m0, s18
	s_nop 0
	global_load_lds_dwordx4 v[162:163], off
	v_lshl_add_u64 v[162:163], s[16:17], 0, v[154:155]
	s_add_i32 m0, s18, 0x2000
	s_nop 0
	global_load_lds_dwordx4 v[162:163], off
	v_lshl_add_u64 v[162:163], v[196:197], 0, s[86:87]
	s_mov_b32 m0, s29
	s_nop 0
	global_load_lds_dwordx4 v[162:163], off
	v_lshl_add_u64 v[162:163], v[208:209], 0, s[86:87]
	s_mov_b32 m0, s30
	s_nop 0
	global_load_lds_dwordx4 v[162:163], off
	s_waitcnt vmcnt(8)
	s_waitcnt lgkmcnt(0)
	s_barrier
	s_setprio 1
	s_waitcnt lgkmcnt(0)
	v_mfma_f32_16x16x32_bf16 v[62:65], v[130:133], v[182:185], v[62:65]
	v_mfma_f32_16x16x32_bf16 v[54:57], v[138:141], v[182:185], v[54:57]
	v_mfma_f32_16x16x32_bf16 v[46:49], v[130:133], v[200:203], v[46:49]
	v_mfma_f32_16x16x32_bf16 v[38:41], v[138:141], v[200:203], v[38:41]
	v_mfma_f32_16x16x32_bf16 v[30:33], v[130:133], v[220:223], v[30:33]
	v_mfma_f32_16x16x32_bf16 v[22:25], v[138:141], v[220:223], v[22:25]
	v_mfma_f32_16x16x32_bf16 v[14:17], v[130:133], v[228:231], v[14:17]
	v_mfma_f32_16x16x32_bf16 v[6:9], v[138:141], v[228:231], v[6:9]
	v_mfma_f32_16x16x32_bf16 v[62:65], v[134:137], v[186:189], v[62:65]
	v_mfma_f32_16x16x32_bf16 v[54:57], v[142:145], v[186:189], v[54:57]
	v_mfma_f32_16x16x32_bf16 v[46:49], v[134:137], v[204:207], v[46:49]
	v_mfma_f32_16x16x32_bf16 v[38:41], v[142:145], v[204:207], v[38:41]
	v_mfma_f32_16x16x32_bf16 v[30:33], v[134:137], v[224:227], v[30:33]
	v_mfma_f32_16x16x32_bf16 v[22:25], v[142:145], v[224:227], v[22:25]
	v_mfma_f32_16x16x32_bf16 v[14:17], v[134:137], v[232:235], v[14:17]
	v_mfma_f32_16x16x32_bf16 v[6:9], v[142:145], v[232:235], v[6:9]
	s_setprio 0
	s_setprio 1
	v_mfma_f32_16x16x32_bf16 v[58:61], v[146:149], v[182:185], v[58:61]
	v_mfma_f32_16x16x32_bf16 v[50:53], v[174:177], v[182:185], v[50:53]
	v_mfma_f32_16x16x32_bf16 v[42:45], v[146:149], v[200:203], v[42:45]
	v_mfma_f32_16x16x32_bf16 v[34:37], v[174:177], v[200:203], v[34:37]
	v_mfma_f32_16x16x32_bf16 v[26:29], v[146:149], v[220:223], v[26:29]
	v_mfma_f32_16x16x32_bf16 v[18:21], v[174:177], v[220:223], v[18:21]
	v_mfma_f32_16x16x32_bf16 v[10:13], v[146:149], v[228:231], v[10:13]
	v_mfma_f32_16x16x32_bf16 v[2:5], v[174:177], v[228:231], v[2:5]
	v_mfma_f32_16x16x32_bf16 v[58:61], v[150:153], v[186:189], v[58:61]
	v_mfma_f32_16x16x32_bf16 v[50:53], v[178:181], v[186:189], v[50:53]
	v_mfma_f32_16x16x32_bf16 v[42:45], v[150:153], v[204:207], v[42:45]
	v_mfma_f32_16x16x32_bf16 v[34:37], v[178:181], v[204:207], v[34:37]
	v_mfma_f32_16x16x32_bf16 v[26:29], v[150:153], v[224:227], v[26:29]
	v_mfma_f32_16x16x32_bf16 v[18:21], v[178:181], v[224:227], v[18:21]
	v_mfma_f32_16x16x32_bf16 v[10:13], v[150:153], v[232:235], v[10:13]
	v_mfma_f32_16x16x32_bf16 v[2:5], v[178:181], v[232:235], v[2:5]
	s_setprio 0
	s_barrier
	s_add_i32 s41, s41, 2
	s_add_u32 s4, s4, 0x100
	s_addc_u32 s5, s5, 0
	s_add_u32 s39, s39, 0x100
	s_addc_u32 s40, s40, 0
	s_cmp_gt_u32 s41, 13
	s_cbranch_scc0 .LBB0_1446
